# v66 + the static s4 assignment is used only when the grid has 256 workgroups; any other grid size falls back to the original atomic task queue
# speedup vs baseline: 1.0002x; 1.0002x over previous
.LBB0_341:
	v_mov_b32_e32 v205, v236
	s_nop 0
	v_cmp_eq_u32_e32 vcc, 0, v205
	s_and_saveexec_b64 s[2:3], vcc
	s_cbranch_execz .LBB0_345
	s_mov_b64 s[6:7], exec
	v_mbcnt_lo_u32_b32 v0, s6, 0
	v_mbcnt_hi_u32_b32 v0, s7, v0
	v_cmp_eq_u32_e32 vcc, 0, v0
	s_and_saveexec_b64 s[4:5], vcc
	s_cbranch_execz .LBB0_344
	s_bcnt1_i32_b64 s6, s[6:7]
	v_mov_b32_e32 v1, s6
	v_readlane_b32 s101, v252, 9
	s_cmpk_eq_u32 s101, 0x100
	s_cbranch_scc1 .Ls4_static
	global_atomic_add v1, v161, v1, s[42:43] sc0
	s_branch .Ls4_deq_done
.Ls4_static:
	v_mov_b32_e32 v1, s100
.Ls4_deq_done:
.LBB0_344:
	s_or_b64 exec, exec, s[4:5]
	s_waitcnt vmcnt(0)
	v_readfirstlane_b32 s4, v1
	s_nop 1
	v_add_u32_e32 v0, s4, v0
	ds_write_b32 v161, v0 offset:8
